# r13 + write-through (sc1) epilogue stores in the short GEMM phases (uq/ukv, w_out, w_down) so the XCC leader's L2 write-back at the grid barrier finds less dirty data
# baseline (speedup 1.0000x reference)
.LBB0_226:
	v_readfirstlane_b32 s52, v145
	s_lshl_b32 s54, s52, 4
	s_lshl_b32 s53, s74, 8
	s_andn2_b32 s54, s54, 63
	v_mbcnt_lo_u32_b32 v140, -1, 0
	v_mbcnt_hi_u32_b32 v140, -1, v140
	s_add_i32 s54, s54, s53
	s_lshl_b32 s52, s52, 5
	v_and_or_b32 v152, v140, 15, s54
	s_lshl_b32 s53, s73, 8
	s_and_b32 s52, s52, 0x60
	v_ashrrev_i32_e32 v140, 1, v140
	v_and_b32_e32 v140, -8, v140
	s_or_b32 s52, s52, s53
	v_add_u32_e32 v142, s52, v140
	v_mov_b64_e32 v[140:141], s[2:3]
	v_ashrrev_i32_e32 v143, 31, v142
	v_mad_i64_i32 v[148:149], s[52:53], v152, s64, v[140:141]
	v_lshlrev_b64 v[142:143], 1, v[142:143]
	v_lshl_add_u64 v[148:149], v[148:149], 0, v[142:143]
	v_pk_mul_f32 v[126:127], v[126:127], s[8:9] op_sel_hi:[1,0]
	v_pk_mul_f32 v[124:125], v[124:125], s[8:9] op_sel_hi:[1,0]
	v_pk_mul_f32 v[150:151], v[122:123], s[8:9] op_sel_hi:[1,0]
	v_pk_mul_f32 v[122:123], v[120:121], s[8:9] op_sel_hi:[1,0]
	v_cvt_pk_bf16_f32 v120, v124, v125
	v_cvt_pk_bf16_f32 v121, v126, v127
	v_pk_mul_f32 v[112:113], v[112:113], s[8:9] op_sel_hi:[1,0]
	v_cvt_pk_bf16_f32 v122, v122, v123
	v_cvt_pk_bf16_f32 v123, v150, v151
	global_store_dwordx4 v[148:149], v[120:123], off sc1
	v_pk_mul_f32 v[114:115], v[114:115], s[8:9] op_sel_hi:[1,0]
	v_pk_mul_f32 v[110:111], v[110:111], s[8:9] op_sel_hi:[1,0]
	v_pk_mul_f32 v[120:121], v[106:107], s[8:9] op_sel_hi:[1,0]
	v_pk_mul_f32 v[106:107], v[104:105], s[8:9] op_sel_hi:[1,0]
	v_cvt_pk_bf16_f32 v104, v112, v113
	v_cvt_pk_bf16_f32 v105, v114, v115
	v_pk_mul_f32 v[108:109], v[108:109], s[8:9] op_sel_hi:[1,0]
	v_cvt_pk_bf16_f32 v106, v106, v107
	v_cvt_pk_bf16_f32 v107, v120, v121
	global_store_dwordx4 v[148:149], v[104:107], off offset:256 sc1
	v_pk_mul_f32 v[96:97], v[96:97], s[8:9] op_sel_hi:[1,0]
	v_pk_mul_f32 v[98:99], v[98:99], s[8:9] op_sel_hi:[1,0]
	v_or_b32_e32 v104, 16, v152
	v_mad_i64_i32 v[104:105], s[52:53], v104, s64, v[140:141]
	v_lshl_add_u64 v[112:113], v[104:105], 0, v[142:143]
	v_pk_mul_f32 v[104:105], v[116:117], s[8:9] op_sel_hi:[1,0]
	v_pk_mul_f32 v[106:107], v[118:119], s[8:9] op_sel_hi:[1,0]
	v_cvt_pk_bf16_f32 v104, v104, v105
	v_pk_mul_f32 v[94:95], v[94:95], s[8:9] op_sel_hi:[1,0]
	v_cvt_pk_bf16_f32 v105, v106, v107
	v_cvt_pk_bf16_f32 v106, v108, v109
	v_cvt_pk_bf16_f32 v107, v110, v111
	global_store_dwordx4 v[112:113], v[104:107], off sc1
	v_pk_mul_f32 v[92:93], v[92:93], s[8:9] op_sel_hi:[1,0]
	v_pk_mul_f32 v[80:81], v[80:81], s[8:9] op_sel_hi:[1,0]
	v_pk_mul_f32 v[104:105], v[90:91], s[8:9] op_sel_hi:[1,0]
	v_pk_mul_f32 v[90:91], v[88:89], s[8:9] op_sel_hi:[1,0]
	v_cvt_pk_bf16_f32 v88, v96, v97
	v_cvt_pk_bf16_f32 v89, v98, v99
	v_pk_mul_f32 v[82:83], v[82:83], s[8:9] op_sel_hi:[1,0]
	v_cvt_pk_bf16_f32 v90, v90, v91
	v_cvt_pk_bf16_f32 v91, v104, v105
	global_store_dwordx4 v[112:113], v[88:91], off offset:256 sc1
	v_pk_mul_f32 v[78:79], v[78:79], s[8:9] op_sel_hi:[1,0]
	v_pk_mul_f32 v[76:77], v[76:77], s[8:9] op_sel_hi:[1,0]
	v_or_b32_e32 v88, 32, v152
	v_mad_i64_i32 v[88:89], s[52:53], v88, s64, v[140:141]
	v_lshl_add_u64 v[96:97], v[88:89], 0, v[142:143]
	v_pk_mul_f32 v[88:89], v[100:101], s[8:9] op_sel_hi:[1,0]
	v_pk_mul_f32 v[90:91], v[102:103], s[8:9] op_sel_hi:[1,0]
	v_cvt_pk_bf16_f32 v88, v88, v89
	v_pk_mul_f32 v[68:69], v[68:69], s[8:9] op_sel_hi:[1,0]
	v_cvt_pk_bf16_f32 v89, v90, v91
	v_cvt_pk_bf16_f32 v90, v92, v93
	v_cvt_pk_bf16_f32 v91, v94, v95
	global_store_dwordx4 v[96:97], v[88:91], off sc1
	v_pk_mul_f32 v[70:71], v[70:71], s[8:9] op_sel_hi:[1,0]
	v_pk_mul_f32 v[62:63], v[62:63], s[8:9] op_sel_hi:[1,0]
	v_pk_mul_f32 v[88:89], v[74:75], s[8:9] op_sel_hi:[1,0]
	v_pk_mul_f32 v[74:75], v[72:73], s[8:9] op_sel_hi:[1,0]
	v_cvt_pk_bf16_f32 v72, v80, v81
	v_cvt_pk_bf16_f32 v73, v82, v83
	v_pk_mul_f32 v[60:61], v[60:61], s[8:9] op_sel_hi:[1,0]
	v_cvt_pk_bf16_f32 v74, v74, v75
	v_cvt_pk_bf16_f32 v75, v88, v89
	global_store_dwordx4 v[96:97], v[72:75], off offset:256 sc1
	v_pk_mul_f32 v[48:49], v[48:49], s[8:9] op_sel_hi:[1,0]
	v_pk_mul_f32 v[50:51], v[50:51], s[8:9] op_sel_hi:[1,0]
	v_or_b32_e32 v72, 48, v152
	v_mad_i64_i32 v[72:73], s[52:53], v72, s64, v[140:141]
	v_lshl_add_u64 v[80:81], v[72:73], 0, v[142:143]
	v_pk_mul_f32 v[72:73], v[84:85], s[8:9] op_sel_hi:[1,0]
	v_pk_mul_f32 v[74:75], v[86:87], s[8:9] op_sel_hi:[1,0]
	v_cvt_pk_bf16_f32 v72, v72, v73
	v_pk_mul_f32 v[46:47], v[46:47], s[8:9] op_sel_hi:[1,0]
	v_cvt_pk_bf16_f32 v73, v74, v75
	v_cvt_pk_bf16_f32 v74, v76, v77
	v_cvt_pk_bf16_f32 v75, v78, v79
	global_store_dwordx4 v[80:81], v[72:75], off sc1
	v_pk_mul_f32 v[44:45], v[44:45], s[8:9] op_sel_hi:[1,0]
	v_pk_mul_f32 v[32:33], v[32:33], s[8:9] op_sel_hi:[1,0]
	v_pk_mul_f32 v[72:73], v[66:67], s[8:9] op_sel_hi:[1,0]
	v_pk_mul_f32 v[66:67], v[64:65], s[8:9] op_sel_hi:[1,0]
	v_cvt_pk_bf16_f32 v64, v68, v69
	v_cvt_pk_bf16_f32 v65, v70, v71
	v_pk_mul_f32 v[34:35], v[34:35], s[8:9] op_sel_hi:[1,0]
	v_cvt_pk_bf16_f32 v66, v66, v67
	v_cvt_pk_bf16_f32 v67, v72, v73
	global_store_dwordx4 v[80:81], v[64:67], off offset:256 sc1
	v_pk_mul_f32 v[30:31], v[30:31], s[8:9] op_sel_hi:[1,0]
	v_pk_mul_f32 v[28:29], v[28:29], s[8:9] op_sel_hi:[1,0]
	v_add_u32_e32 v64, 0x80, v152
	v_mad_i64_i32 v[64:65], s[52:53], v64, s64, v[140:141]
	v_lshl_add_u64 v[64:65], v[64:65], 0, v[142:143]
	v_pk_mul_f32 v[66:67], v[58:59], s[8:9] op_sel_hi:[1,0]
	v_pk_mul_f32 v[58:59], v[56:57], s[8:9] op_sel_hi:[1,0]
	v_cvt_pk_bf16_f32 v56, v60, v61
	v_cvt_pk_bf16_f32 v57, v62, v63
	v_pk_mul_f32 v[16:17], v[16:17], s[8:9] op_sel_hi:[1,0]
	v_cvt_pk_bf16_f32 v58, v58, v59
	v_cvt_pk_bf16_f32 v59, v66, v67
	global_store_dwordx4 v[64:65], v[56:59], off sc1
	v_pk_mul_f32 v[18:19], v[18:19], s[8:9] op_sel_hi:[1,0]
	v_pk_mul_f32 v[14:15], v[14:15], s[8:9] op_sel_hi:[1,0]
	v_pk_mul_f32 v[56:57], v[42:43], s[8:9] op_sel_hi:[1,0]
	v_pk_mul_f32 v[42:43], v[40:41], s[8:9] op_sel_hi:[1,0]
	v_cvt_pk_bf16_f32 v40, v48, v49
	v_cvt_pk_bf16_f32 v41, v50, v51
	v_pk_mul_f32 v[12:13], v[12:13], s[8:9] op_sel_hi:[1,0]
	v_cvt_pk_bf16_f32 v42, v42, v43
	v_cvt_pk_bf16_f32 v43, v56, v57
	global_store_dwordx4 v[64:65], v[40:43], off offset:256 sc1
	s_and_b64 vcc, exec, s[10:11]
	s_mov_b32 s74, s66
	v_add_u32_e32 v40, 0x90, v152
	v_mad_i64_i32 v[40:41], s[52:53], v40, s64, v[140:141]
	v_lshl_add_u64 v[48:49], v[40:41], 0, v[142:143]
	v_pk_mul_f32 v[40:41], v[52:53], s[8:9] op_sel_hi:[1,0]
	v_pk_mul_f32 v[42:43], v[54:55], s[8:9] op_sel_hi:[1,0]
	v_cvt_pk_bf16_f32 v40, v40, v41
	s_mov_b32 s73, s65
	v_cvt_pk_bf16_f32 v41, v42, v43
	v_cvt_pk_bf16_f32 v42, v44, v45
	v_cvt_pk_bf16_f32 v43, v46, v47
	global_store_dwordx4 v[48:49], v[40:43], off sc1
	s_mov_b32 s54, s72
	v_pk_mul_f32 v[6:7], v[6:7], s[8:9] op_sel_hi:[1,0]
	v_pk_mul_f32 v[40:41], v[26:27], s[8:9] op_sel_hi:[1,0]
	v_pk_mul_f32 v[26:27], v[24:25], s[8:9] op_sel_hi:[1,0]
	v_cvt_pk_bf16_f32 v24, v32, v33
	v_cvt_pk_bf16_f32 v25, v34, v35
	v_pk_mul_f32 v[4:5], v[4:5], s[8:9] op_sel_hi:[1,0]
	v_cvt_pk_bf16_f32 v26, v26, v27
	v_cvt_pk_bf16_f32 v27, v40, v41
	global_store_dwordx4 v[48:49], v[24:27], off offset:256 sc1
	s_nop 1
	v_add_u32_e32 v24, 0xa0, v152
	v_mad_i64_i32 v[24:25], s[52:53], v24, s64, v[140:141]
	v_lshl_add_u64 v[32:33], v[24:25], 0, v[142:143]
	v_pk_mul_f32 v[24:25], v[36:37], s[8:9] op_sel_hi:[1,0]
	v_pk_mul_f32 v[26:27], v[38:39], s[8:9] op_sel_hi:[1,0]
	v_cvt_pk_bf16_f32 v24, v24, v25
	s_nop 0
	v_cvt_pk_bf16_f32 v25, v26, v27
	v_cvt_pk_bf16_f32 v26, v28, v29
	v_cvt_pk_bf16_f32 v27, v30, v31
	global_store_dwordx4 v[32:33], v[24:27], off sc1
	s_nop 1
	v_pk_mul_f32 v[24:25], v[10:11], s[8:9] op_sel_hi:[1,0]
	v_pk_mul_f32 v[10:11], v[8:9], s[8:9] op_sel_hi:[1,0]
	v_cvt_pk_bf16_f32 v8, v16, v17
	v_cvt_pk_bf16_f32 v9, v18, v19
	s_nop 0
	v_cvt_pk_bf16_f32 v10, v10, v11
	v_cvt_pk_bf16_f32 v11, v24, v25
	global_store_dwordx4 v[32:33], v[8:11], off offset:256 sc1
	s_nop 1
	v_add_u32_e32 v8, 0xb0, v152
	v_mad_i64_i32 v[8:9], s[52:53], v8, s64, v[140:141]
	v_lshl_add_u64 v[16:17], v[8:9], 0, v[142:143]
	v_pk_mul_f32 v[8:9], v[20:21], s[8:9] op_sel_hi:[1,0]
	v_pk_mul_f32 v[10:11], v[22:23], s[8:9] op_sel_hi:[1,0]
	v_cvt_pk_bf16_f32 v8, v8, v9
	s_mov_b32 s52, s67
	v_cvt_pk_bf16_f32 v9, v10, v11
	v_cvt_pk_bf16_f32 v10, v12, v13
	v_cvt_pk_bf16_f32 v11, v14, v15
	global_store_dwordx4 v[16:17], v[8:11], off sc1
	s_nop 1
	v_pk_mul_f32 v[8:9], v[2:3], s[8:9] op_sel_hi:[1,0]
	v_pk_mul_f32 v[2:3], v[0:1], s[8:9] op_sel_hi:[1,0]
	v_cvt_pk_bf16_f32 v0, v4, v5
	v_cvt_pk_bf16_f32 v1, v6, v7
	s_nop 0
	v_cvt_pk_bf16_f32 v2, v2, v3
	v_cvt_pk_bf16_f32 v3, v8, v9
	global_store_dwordx4 v[16:17], v[0:3], off offset:256 sc1
	s_cbranch_vccnz .LBB0_233

.LBB0_238:
	v_readfirstlane_b32 s11, v140
	s_lshl_b32 s53, s11, 4
	s_andn2_b32 s53, s53, 63
	v_mbcnt_lo_u32_b32 v137, -1, 0
	v_mbcnt_hi_u32_b32 v137, -1, v137
	s_add_i32 s53, s53, s52
	s_lshl_b32 s11, s11, 5
	v_and_or_b32 v136, v137, 15, s53
	s_and_b32 s11, s11, 0x60
	v_ashrrev_i32_e32 v137, 1, v137
	v_and_b32_e32 v137, -8, v137
	s_or_b32 s10, s11, s10
	v_add_u32_e32 v138, s10, v137
	v_ashrrev_i32_e32 v137, 31, v136
	v_lshlrev_b64 v[144:145], 11, v[136:137]
	v_ashrrev_i32_e32 v139, 31, v138
	v_lshl_add_u64 v[144:145], s[4:5], 0, v[144:145]
	v_lshlrev_b64 v[138:139], 1, v[138:139]
	v_lshl_add_u64 v[144:145], v[144:145], 0, v[138:139]
	v_cvt_pk_bf16_f32 v116, v116, v117
	v_cvt_pk_bf16_f32 v117, v118, v119
	v_cvt_pk_bf16_f32 v118, v112, v113
	v_cvt_pk_bf16_f32 v112, v124, v125
	v_cvt_pk_bf16_f32 v119, v114, v115
	v_cvt_pk_bf16_f32 v113, v126, v127
	v_cvt_pk_bf16_f32 v114, v120, v121
	v_cvt_pk_bf16_f32 v115, v122, v123
	global_store_dwordx4 v[144:145], v[112:115], off offset:256 sc1
	v_cvt_pk_bf16_f32 v100, v100, v101
	v_cvt_pk_bf16_f32 v101, v102, v103
	v_cvt_pk_bf16_f32 v102, v96, v97
	v_cvt_pk_bf16_f32 v96, v108, v109
	v_cvt_pk_bf16_f32 v103, v98, v99
	s_nop 1
	v_or_b32_e32 v112, 16, v136
	v_ashrrev_i32_e32 v113, 31, v112
	v_lshlrev_b64 v[112:113], 11, v[112:113]
	v_lshl_add_u64 v[112:113], s[4:5], 0, v[112:113]
	v_lshl_add_u64 v[112:113], v[112:113], 0, v[138:139]
	v_cvt_pk_bf16_f32 v97, v110, v111
	v_cvt_pk_bf16_f32 v98, v104, v105
	v_cvt_pk_bf16_f32 v99, v106, v107
	global_store_dwordx4 v[112:113], v[96:99], off offset:256 sc1
	v_cvt_pk_bf16_f32 v84, v84, v85
	v_cvt_pk_bf16_f32 v85, v86, v87
	v_cvt_pk_bf16_f32 v86, v80, v81
	v_cvt_pk_bf16_f32 v80, v92, v93
	v_cvt_pk_bf16_f32 v87, v82, v83
	s_nop 1
	v_or_b32_e32 v96, 32, v136
	v_ashrrev_i32_e32 v97, 31, v96
	v_lshlrev_b64 v[96:97], 11, v[96:97]
	v_lshl_add_u64 v[96:97], s[4:5], 0, v[96:97]
	v_lshl_add_u64 v[96:97], v[96:97], 0, v[138:139]
	v_cvt_pk_bf16_f32 v81, v94, v95
	v_cvt_pk_bf16_f32 v82, v88, v89
	v_cvt_pk_bf16_f32 v83, v90, v91
	global_store_dwordx4 v[96:97], v[80:83], off offset:256 sc1
	v_cvt_pk_bf16_f32 v60, v60, v61
	v_cvt_pk_bf16_f32 v61, v62, v63
	v_cvt_pk_bf16_f32 v62, v48, v49
	v_cvt_pk_bf16_f32 v48, v76, v77
	v_cvt_pk_bf16_f32 v63, v50, v51
	s_nop 1
	v_or_b32_e32 v80, 48, v136
	v_ashrrev_i32_e32 v81, 31, v80
	v_lshlrev_b64 v[80:81], 11, v[80:81]
	v_lshl_add_u64 v[80:81], s[4:5], 0, v[80:81]
	v_lshl_add_u64 v[80:81], v[80:81], 0, v[138:139]
	v_cvt_pk_bf16_f32 v49, v78, v79
	v_cvt_pk_bf16_f32 v50, v72, v73
	v_cvt_pk_bf16_f32 v51, v74, v75
	global_store_dwordx4 v[80:81], v[48:51], off offset:256 sc1
	global_store_dwordx4 v[80:81], v[60:63], off sc1
	v_cvt_pk_bf16_f32 v40, v40, v41
	v_cvt_pk_bf16_f32 v41, v42, v43
	v_cvt_pk_bf16_f32 v42, v32, v33
	v_cvt_pk_bf16_f32 v32, v44, v45
	s_nop 0
	v_add_u32_e32 v48, 0x80, v136
	v_ashrrev_i32_e32 v49, 31, v48
	v_lshlrev_b64 v[48:49], 11, v[48:49]
	v_lshl_add_u64 v[48:49], s[4:5], 0, v[48:49]
	v_lshl_add_u64 v[60:61], v[48:49], 0, v[138:139]
	v_cvt_pk_bf16_f32 v48, v64, v65
	v_cvt_pk_bf16_f32 v49, v66, v67
	v_cvt_pk_bf16_f32 v50, v52, v53
	v_cvt_pk_bf16_f32 v51, v54, v55
	global_store_dwordx4 v[60:61], v[48:51], off sc1
	v_cvt_pk_bf16_f32 v43, v34, v35
	v_cvt_pk_bf16_f32 v33, v46, v47
	v_cvt_pk_bf16_f32 v34, v36, v37
	v_cvt_pk_bf16_f32 v35, v38, v39
	v_cvt_pk_bf16_f32 v24, v24, v25
	s_nop 1
	v_cvt_pk_bf16_f32 v48, v68, v69
	v_cvt_pk_bf16_f32 v49, v70, v71
	v_cvt_pk_bf16_f32 v50, v56, v57
	v_cvt_pk_bf16_f32 v51, v58, v59
	global_store_dwordx4 v[60:61], v[48:51], off offset:256 sc1
	v_cvt_pk_bf16_f32 v25, v26, v27
	v_cvt_pk_bf16_f32 v26, v16, v17
	v_cvt_pk_bf16_f32 v16, v28, v29
	v_cvt_pk_bf16_f32 v27, v18, v19
	v_cvt_pk_bf16_f32 v17, v30, v31
	s_nop 1
	v_add_u32_e32 v48, 0x90, v136
	v_ashrrev_i32_e32 v49, 31, v48
	v_lshlrev_b64 v[48:49], 11, v[48:49]
	v_lshl_add_u64 v[48:49], s[4:5], 0, v[48:49]
	v_lshl_add_u64 v[48:49], v[48:49], 0, v[138:139]
	global_store_dwordx4 v[48:49], v[32:35], off offset:256 sc1
	v_cvt_pk_bf16_f32 v18, v20, v21
	v_cvt_pk_bf16_f32 v19, v22, v23
	s_andn2_b64 vcc, exec, s[8:9]
	global_store_dwordx4 v[144:145], v[116:119], off sc1
	v_add_u32_e32 v32, 0xa0, v136
	v_ashrrev_i32_e32 v33, 31, v32
	v_lshlrev_b64 v[32:33], 11, v[32:33]
	v_lshl_add_u64 v[32:33], s[4:5], 0, v[32:33]
	v_lshl_add_u64 v[32:33], v[32:33], 0, v[138:139]
	global_store_dwordx4 v[32:33], v[16:19], off offset:256 sc1
	global_store_dwordx4 v[112:113], v[100:103], off sc1
	global_store_dwordx4 v[96:97], v[84:87], off sc1
	v_add_u32_e32 v16, 0xb0, v136
	v_ashrrev_i32_e32 v17, 31, v16
	v_lshlrev_b64 v[16:17], 11, v[16:17]
	v_lshl_add_u64 v[16:17], s[4:5], 0, v[16:17]
	v_lshl_add_u64 v[16:17], v[16:17], 0, v[138:139]
	global_store_dwordx4 v[48:49], v[40:43], off sc1
	global_store_dwordx4 v[32:33], v[24:27], off sc1
	v_cvt_pk_bf16_f32 v8, v8, v9
	v_cvt_pk_bf16_f32 v9, v10, v11
	v_cvt_pk_bf16_f32 v10, v0, v1
	v_cvt_pk_bf16_f32 v11, v2, v3
	global_store_dwordx4 v[16:17], v[8:11], off sc1
	v_cvt_pk_bf16_f32 v0, v12, v13
	v_cvt_pk_bf16_f32 v1, v14, v15
	v_cvt_pk_bf16_f32 v2, v4, v5
	v_cvt_pk_bf16_f32 v3, v6, v7
	global_store_dwordx4 v[16:17], v[0:3], off offset:256 sc1
	s_cbranch_vccz .LBB0_245

.LBB0_317:
	v_readfirstlane_b32 s2, v145
	s_lshl_b32 s11, s2, 4
	s_lshl_b32 s10, s66, 8
	s_andn2_b32 s11, s11, 63
	v_mbcnt_lo_u32_b32 v141, -1, 0
	v_mbcnt_hi_u32_b32 v141, -1, v141
	s_add_i32 s11, s11, s10
	s_lshl_b32 s2, s2, 5
	v_and_or_b32 v140, v141, 15, s11
	s_lshl_b32 s10, s65, 8
	s_and_b32 s2, s2, 0x60
	v_ashrrev_i32_e32 v141, 1, v141
	v_and_b32_e32 v141, -8, v141
	s_or_b32 s2, s2, s10
	v_cvt_pk_bf16_f32 v68, v68, v69
	v_cvt_pk_bf16_f32 v69, v70, v71
	v_cvt_pk_bf16_f32 v70, v64, v65
	v_add_u32_e32 v64, 0x80, v140
	v_add_u32_e32 v142, s2, v141
	v_ashrrev_i32_e32 v141, 31, v140
	v_cvt_pk_bf16_f32 v108, v108, v109
	v_cvt_pk_bf16_f32 v109, v110, v111
	v_cvt_pk_bf16_f32 v110, v104, v105
	v_or_b32_e32 v104, 16, v140
	v_ashrrev_i32_e32 v65, 31, v64
	v_cvt_pk_bf16_f32 v44, v44, v45
	v_cvt_pk_bf16_f32 v45, v46, v47
	v_cvt_pk_bf16_f32 v46, v40, v41
	v_add_u32_e32 v40, 0x90, v140
	v_lshlrev_b64 v[148:149], 11, v[140:141]
	v_ashrrev_i32_e32 v143, 31, v142
	v_ashrrev_i32_e32 v105, 31, v104
	v_cvt_pk_bf16_f32 v92, v92, v93
	v_cvt_pk_bf16_f32 v93, v94, v95
	v_cvt_pk_bf16_f32 v94, v88, v89
	v_or_b32_e32 v88, 32, v140
	v_lshlrev_b64 v[64:65], 11, v[64:65]
	v_ashrrev_i32_e32 v41, 31, v40
	v_cvt_pk_bf16_f32 v28, v28, v29
	v_cvt_pk_bf16_f32 v29, v30, v31
	v_cvt_pk_bf16_f32 v30, v24, v25
	v_add_u32_e32 v24, 0xa0, v140
	v_lshl_add_u64 v[148:149], s[0:1], 0, v[148:149]
	v_lshlrev_b64 v[142:143], 1, v[142:143]
	v_lshlrev_b64 v[104:105], 11, v[104:105]
	v_ashrrev_i32_e32 v89, 31, v88
	v_cvt_pk_bf16_f32 v76, v76, v77
	v_cvt_pk_bf16_f32 v77, v78, v79
	v_cvt_pk_bf16_f32 v78, v72, v73
	v_or_b32_e32 v72, 48, v140
	v_lshl_add_u64 v[64:65], s[0:1], 0, v[64:65]
	v_lshlrev_b64 v[40:41], 11, v[40:41]
	v_ashrrev_i32_e32 v25, 31, v24
	v_cvt_pk_bf16_f32 v12, v12, v13
	v_cvt_pk_bf16_f32 v13, v14, v15
	v_cvt_pk_bf16_f32 v14, v8, v9
	v_add_u32_e32 v8, 0xb0, v140
	v_lshl_add_u64 v[148:149], v[148:149], 0, v[142:143]
	v_lshl_add_u64 v[104:105], s[0:1], 0, v[104:105]
	v_lshlrev_b64 v[88:89], 11, v[88:89]
	v_ashrrev_i32_e32 v73, 31, v72
	v_lshl_add_u64 v[64:65], v[64:65], 0, v[142:143]
	v_lshl_add_u64 v[40:41], s[0:1], 0, v[40:41]
	v_lshlrev_b64 v[24:25], 11, v[24:25]
	v_ashrrev_i32_e32 v9, 31, v8
	v_cvt_pk_bf16_f32 v111, v106, v107
	global_store_dwordx4 v[148:149], v[108:111], off offset:256 sc1
	v_lshl_add_u64 v[88:89], s[0:1], 0, v[88:89]
	v_lshlrev_b64 v[72:73], 11, v[72:73]
	v_lshl_add_u64 v[108:109], v[104:105], 0, v[142:143]
	v_cvt_pk_bf16_f32 v47, v42, v43
	global_store_dwordx4 v[64:65], v[44:47], off offset:256 sc1
	v_lshl_add_u64 v[24:25], s[0:1], 0, v[24:25]
	v_lshlrev_b64 v[8:9], 11, v[8:9]
	v_lshl_add_u64 v[44:45], v[40:41], 0, v[142:143]
	v_cvt_pk_bf16_f32 v95, v90, v91
	global_store_dwordx4 v[108:109], v[92:95], off offset:256 sc1
	v_lshl_add_u64 v[72:73], s[0:1], 0, v[72:73]
	v_cvt_pk_bf16_f32 v31, v26, v27
	global_store_dwordx4 v[44:45], v[28:31], off offset:256 sc1
	v_lshl_add_u64 v[92:93], v[88:89], 0, v[142:143]
	v_lshl_add_u64 v[8:9], s[0:1], 0, v[8:9]
	v_lshl_add_u64 v[28:29], v[24:25], 0, v[142:143]
	v_cvt_pk_bf16_f32 v79, v74, v75
	global_store_dwordx4 v[92:93], v[76:79], off offset:256 sc1
	v_cvt_pk_bf16_f32 v15, v10, v11
	global_store_dwordx4 v[28:29], v[12:15], off offset:256 sc1
	s_and_b64 vcc, exec, s[8:9]
	v_lshl_add_u64 v[76:77], v[72:73], 0, v[142:143]
	v_lshl_add_u64 v[12:13], v[8:9], 0, v[142:143]
	s_mov_b32 s66, s72
	s_mov_b32 s65, s67
	s_mov_b32 s10, s73
	s_mov_b32 s52, s74
	v_cvt_pk_bf16_f32 v124, v124, v125
	v_cvt_pk_bf16_f32 v125, v126, v127
	v_cvt_pk_bf16_f32 v126, v120, v121
	v_cvt_pk_bf16_f32 v127, v122, v123
	global_store_dwordx4 v[148:149], v[124:127], off sc1
	v_cvt_pk_bf16_f32 v104, v116, v117
	v_cvt_pk_bf16_f32 v105, v118, v119
	v_cvt_pk_bf16_f32 v106, v112, v113
	v_cvt_pk_bf16_f32 v107, v114, v115
	global_store_dwordx4 v[108:109], v[104:107], off sc1
	v_cvt_pk_bf16_f32 v88, v100, v101
	v_cvt_pk_bf16_f32 v89, v102, v103
	v_cvt_pk_bf16_f32 v90, v96, v97
	v_cvt_pk_bf16_f32 v91, v98, v99
	global_store_dwordx4 v[92:93], v[88:91], off sc1
	v_cvt_pk_bf16_f32 v72, v84, v85
	v_cvt_pk_bf16_f32 v73, v86, v87
	v_cvt_pk_bf16_f32 v74, v80, v81
	v_cvt_pk_bf16_f32 v75, v82, v83
	global_store_dwordx4 v[76:77], v[72:75], off sc1
	v_cvt_pk_bf16_f32 v71, v66, v67
	global_store_dwordx4 v[76:77], v[68:71], off offset:256 sc1
	v_cvt_pk_bf16_f32 v60, v60, v61
	v_cvt_pk_bf16_f32 v61, v62, v63
	v_cvt_pk_bf16_f32 v62, v56, v57
	v_cvt_pk_bf16_f32 v63, v58, v59
	global_store_dwordx4 v[64:65], v[60:63], off sc1
	v_cvt_pk_bf16_f32 v40, v52, v53
	v_cvt_pk_bf16_f32 v41, v54, v55
	v_cvt_pk_bf16_f32 v42, v48, v49
	v_cvt_pk_bf16_f32 v43, v50, v51
	global_store_dwordx4 v[44:45], v[40:43], off sc1
	v_cvt_pk_bf16_f32 v24, v36, v37
	v_cvt_pk_bf16_f32 v25, v38, v39
	v_cvt_pk_bf16_f32 v26, v32, v33
	v_cvt_pk_bf16_f32 v27, v34, v35
	global_store_dwordx4 v[28:29], v[24:27], off sc1
	v_cvt_pk_bf16_f32 v8, v20, v21
	v_cvt_pk_bf16_f32 v9, v22, v23
	v_cvt_pk_bf16_f32 v10, v16, v17
	v_cvt_pk_bf16_f32 v11, v18, v19
	global_store_dwordx4 v[12:13], v[8:11], off sc1
	v_cvt_pk_bf16_f32 v4, v4, v5
	v_cvt_pk_bf16_f32 v5, v6, v7
	v_cvt_pk_bf16_f32 v6, v0, v1
	v_cvt_pk_bf16_f32 v7, v2, v3
	global_store_dwordx4 v[12:13], v[4:7], off offset:256 sc1
	s_cbranch_vccnz .LBB0_324

.LBB0_388:
	v_readfirstlane_b32 s2, v145
	s_lshl_b32 s9, s2, 4
	s_lshl_b32 s8, s60, 8
	s_andn2_b32 s9, s9, 63
	v_mbcnt_lo_u32_b32 v141, -1, 0
	v_mbcnt_hi_u32_b32 v141, -1, v141
	s_add_i32 s9, s9, s8
	s_lshl_b32 s2, s2, 5
	v_and_or_b32 v140, v141, 15, s9
	s_lshl_b32 s8, s59, 8
	s_and_b32 s2, s2, 0x60
	v_ashrrev_i32_e32 v141, 1, v141
	v_and_b32_e32 v141, -8, v141
	s_or_b32 s2, s2, s8
	v_cvt_pk_bf16_f32 v68, v68, v69
	v_cvt_pk_bf16_f32 v69, v70, v71
	v_cvt_pk_bf16_f32 v70, v64, v65
	v_add_u32_e32 v64, 0x80, v140
	v_add_u32_e32 v142, s2, v141
	v_ashrrev_i32_e32 v141, 31, v140
	v_cvt_pk_bf16_f32 v108, v108, v109
	v_cvt_pk_bf16_f32 v109, v110, v111
	v_cvt_pk_bf16_f32 v110, v104, v105
	v_or_b32_e32 v104, 16, v140
	v_ashrrev_i32_e32 v65, 31, v64
	v_cvt_pk_bf16_f32 v44, v44, v45
	v_cvt_pk_bf16_f32 v45, v46, v47
	v_cvt_pk_bf16_f32 v46, v40, v41
	v_add_u32_e32 v40, 0x90, v140
	v_lshlrev_b64 v[148:149], 11, v[140:141]
	v_ashrrev_i32_e32 v143, 31, v142
	v_ashrrev_i32_e32 v105, 31, v104
	v_cvt_pk_bf16_f32 v92, v92, v93
	v_cvt_pk_bf16_f32 v93, v94, v95
	v_cvt_pk_bf16_f32 v94, v88, v89
	v_or_b32_e32 v88, 32, v140
	v_lshlrev_b64 v[64:65], 11, v[64:65]
	v_ashrrev_i32_e32 v41, 31, v40
	v_cvt_pk_bf16_f32 v28, v28, v29
	v_cvt_pk_bf16_f32 v29, v30, v31
	v_cvt_pk_bf16_f32 v30, v24, v25
	v_add_u32_e32 v24, 0xa0, v140
	v_lshl_add_u64 v[148:149], s[0:1], 0, v[148:149]
	v_lshlrev_b64 v[142:143], 1, v[142:143]
	v_lshlrev_b64 v[104:105], 11, v[104:105]
	v_ashrrev_i32_e32 v89, 31, v88
	v_cvt_pk_bf16_f32 v76, v76, v77
	v_cvt_pk_bf16_f32 v77, v78, v79
	v_cvt_pk_bf16_f32 v78, v72, v73
	v_or_b32_e32 v72, 48, v140
	v_lshl_add_u64 v[64:65], s[0:1], 0, v[64:65]
	v_lshlrev_b64 v[40:41], 11, v[40:41]
	v_ashrrev_i32_e32 v25, 31, v24
	v_cvt_pk_bf16_f32 v12, v12, v13
	v_cvt_pk_bf16_f32 v13, v14, v15
	v_cvt_pk_bf16_f32 v14, v8, v9
	v_add_u32_e32 v8, 0xb0, v140
	v_lshl_add_u64 v[148:149], v[148:149], 0, v[142:143]
	v_lshl_add_u64 v[104:105], s[0:1], 0, v[104:105]
	v_lshlrev_b64 v[88:89], 11, v[88:89]
	v_ashrrev_i32_e32 v73, 31, v72
	v_lshl_add_u64 v[64:65], v[64:65], 0, v[142:143]
	v_lshl_add_u64 v[40:41], s[0:1], 0, v[40:41]
	v_lshlrev_b64 v[24:25], 11, v[24:25]
	v_ashrrev_i32_e32 v9, 31, v8
	v_cvt_pk_bf16_f32 v111, v106, v107
	global_store_dwordx4 v[148:149], v[108:111], off offset:256 sc1
	v_lshl_add_u64 v[88:89], s[0:1], 0, v[88:89]
	v_lshlrev_b64 v[72:73], 11, v[72:73]
	v_lshl_add_u64 v[108:109], v[104:105], 0, v[142:143]
	v_cvt_pk_bf16_f32 v47, v42, v43
	global_store_dwordx4 v[64:65], v[44:47], off offset:256 sc1
	v_lshl_add_u64 v[24:25], s[0:1], 0, v[24:25]
	v_lshlrev_b64 v[8:9], 11, v[8:9]
	v_lshl_add_u64 v[44:45], v[40:41], 0, v[142:143]
	v_cvt_pk_bf16_f32 v95, v90, v91
	global_store_dwordx4 v[108:109], v[92:95], off offset:256 sc1
	v_lshl_add_u64 v[72:73], s[0:1], 0, v[72:73]
	v_cvt_pk_bf16_f32 v31, v26, v27
	global_store_dwordx4 v[44:45], v[28:31], off offset:256 sc1
	v_lshl_add_u64 v[92:93], v[88:89], 0, v[142:143]
	v_lshl_add_u64 v[8:9], s[0:1], 0, v[8:9]
	v_lshl_add_u64 v[28:29], v[24:25], 0, v[142:143]
	v_cvt_pk_bf16_f32 v79, v74, v75
	global_store_dwordx4 v[92:93], v[76:79], off offset:256 sc1
	v_cvt_pk_bf16_f32 v15, v10, v11
	global_store_dwordx4 v[28:29], v[12:15], off offset:256 sc1
	s_and_b64 vcc, exec, s[6:7]
	v_lshl_add_u64 v[76:77], v[72:73], 0, v[142:143]
	v_lshl_add_u64 v[12:13], v[8:9], 0, v[142:143]
	s_mov_b32 s60, s62
	s_mov_b32 s59, s61
	s_mov_b32 s8, s63
	s_mov_b32 s10, s64
	v_cvt_pk_bf16_f32 v124, v124, v125
	v_cvt_pk_bf16_f32 v125, v126, v127
	v_cvt_pk_bf16_f32 v126, v120, v121
	v_cvt_pk_bf16_f32 v127, v122, v123
	global_store_dwordx4 v[148:149], v[124:127], off sc1
	v_cvt_pk_bf16_f32 v104, v116, v117
	v_cvt_pk_bf16_f32 v105, v118, v119
	v_cvt_pk_bf16_f32 v106, v112, v113
	v_cvt_pk_bf16_f32 v107, v114, v115
	global_store_dwordx4 v[108:109], v[104:107], off sc1
	v_cvt_pk_bf16_f32 v88, v100, v101
	v_cvt_pk_bf16_f32 v89, v102, v103
	v_cvt_pk_bf16_f32 v90, v96, v97
	v_cvt_pk_bf16_f32 v91, v98, v99
	global_store_dwordx4 v[92:93], v[88:91], off sc1
	v_cvt_pk_bf16_f32 v72, v84, v85
	v_cvt_pk_bf16_f32 v73, v86, v87
	v_cvt_pk_bf16_f32 v74, v80, v81
	v_cvt_pk_bf16_f32 v75, v82, v83
	global_store_dwordx4 v[76:77], v[72:75], off sc1
	v_cvt_pk_bf16_f32 v71, v66, v67
	global_store_dwordx4 v[76:77], v[68:71], off offset:256 sc1
	v_cvt_pk_bf16_f32 v60, v60, v61
	v_cvt_pk_bf16_f32 v61, v62, v63
	v_cvt_pk_bf16_f32 v62, v56, v57
	v_cvt_pk_bf16_f32 v63, v58, v59
	global_store_dwordx4 v[64:65], v[60:63], off sc1
	v_cvt_pk_bf16_f32 v40, v52, v53
	v_cvt_pk_bf16_f32 v41, v54, v55
	v_cvt_pk_bf16_f32 v42, v48, v49
	v_cvt_pk_bf16_f32 v43, v50, v51
	global_store_dwordx4 v[44:45], v[40:43], off sc1
	v_cvt_pk_bf16_f32 v24, v36, v37
	v_cvt_pk_bf16_f32 v25, v38, v39
	v_cvt_pk_bf16_f32 v26, v32, v33
	v_cvt_pk_bf16_f32 v27, v34, v35
	global_store_dwordx4 v[28:29], v[24:27], off sc1
	v_cvt_pk_bf16_f32 v8, v20, v21
	v_cvt_pk_bf16_f32 v9, v22, v23
	v_cvt_pk_bf16_f32 v10, v16, v17
	v_cvt_pk_bf16_f32 v11, v18, v19
	global_store_dwordx4 v[12:13], v[8:11], off sc1
	v_cvt_pk_bf16_f32 v4, v4, v5
	v_cvt_pk_bf16_f32 v5, v6, v7
	v_cvt_pk_bf16_f32 v6, v0, v1
	v_cvt_pk_bf16_f32 v7, v2, v3
	global_store_dwordx4 v[12:13], v[4:7], off offset:256 sc1
	s_cbranch_vccnz .LBB0_395

.LBB0_605:
	v_readfirstlane_b32 s20, v145
	s_lshl_b32 s26, s20, 4
	s_lshl_b32 s21, s54, 8
	s_andn2_b32 s26, s26, 63
	v_mbcnt_lo_u32_b32 v140, -1, 0
	v_mbcnt_hi_u32_b32 v140, -1, v140
	s_add_i32 s26, s26, s21
	s_lshl_b32 s20, s20, 5
	v_and_or_b32 v152, v140, 15, s26
	s_lshl_b32 s21, s53, 8
	s_and_b32 s20, s20, 0x60
	v_ashrrev_i32_e32 v140, 1, v140
	v_and_b32_e32 v140, -8, v140
	s_or_b32 s20, s20, s21
	v_add_u32_e32 v142, s20, v140
	v_mov_b64_e32 v[140:141], s[2:3]
	v_ashrrev_i32_e32 v143, 31, v142
	v_mad_i64_i32 v[148:149], s[20:21], v152, s48, v[140:141]
	v_lshlrev_b64 v[142:143], 1, v[142:143]
	v_lshl_add_u64 v[148:149], v[148:149], 0, v[142:143]
	v_pk_mul_f32 v[126:127], v[126:127], s[8:9] op_sel_hi:[1,0]
	v_pk_mul_f32 v[124:125], v[124:125], s[8:9] op_sel_hi:[1,0]
	v_pk_mul_f32 v[150:151], v[122:123], s[8:9] op_sel_hi:[1,0]
	v_pk_mul_f32 v[122:123], v[120:121], s[8:9] op_sel_hi:[1,0]
	v_cvt_pk_bf16_f32 v120, v124, v125
	v_cvt_pk_bf16_f32 v121, v126, v127
	v_pk_mul_f32 v[112:113], v[112:113], s[8:9] op_sel_hi:[1,0]
	v_cvt_pk_bf16_f32 v122, v122, v123
	v_cvt_pk_bf16_f32 v123, v150, v151
	global_store_dwordx4 v[148:149], v[120:123], off sc1
	v_pk_mul_f32 v[114:115], v[114:115], s[8:9] op_sel_hi:[1,0]
	v_pk_mul_f32 v[110:111], v[110:111], s[8:9] op_sel_hi:[1,0]
	v_pk_mul_f32 v[120:121], v[106:107], s[8:9] op_sel_hi:[1,0]
	v_pk_mul_f32 v[106:107], v[104:105], s[8:9] op_sel_hi:[1,0]
	v_cvt_pk_bf16_f32 v104, v112, v113
	v_cvt_pk_bf16_f32 v105, v114, v115
	v_pk_mul_f32 v[108:109], v[108:109], s[8:9] op_sel_hi:[1,0]
	v_cvt_pk_bf16_f32 v106, v106, v107
	v_cvt_pk_bf16_f32 v107, v120, v121
	global_store_dwordx4 v[148:149], v[104:107], off offset:256 sc1
	v_pk_mul_f32 v[96:97], v[96:97], s[8:9] op_sel_hi:[1,0]
	v_pk_mul_f32 v[98:99], v[98:99], s[8:9] op_sel_hi:[1,0]
	v_or_b32_e32 v104, 16, v152
	v_mad_i64_i32 v[104:105], s[20:21], v104, s48, v[140:141]
	v_lshl_add_u64 v[112:113], v[104:105], 0, v[142:143]
	v_pk_mul_f32 v[104:105], v[116:117], s[8:9] op_sel_hi:[1,0]
	v_pk_mul_f32 v[106:107], v[118:119], s[8:9] op_sel_hi:[1,0]
	v_cvt_pk_bf16_f32 v104, v104, v105
	v_pk_mul_f32 v[94:95], v[94:95], s[8:9] op_sel_hi:[1,0]
	v_cvt_pk_bf16_f32 v105, v106, v107
	v_cvt_pk_bf16_f32 v106, v108, v109
	v_cvt_pk_bf16_f32 v107, v110, v111
	global_store_dwordx4 v[112:113], v[104:107], off sc1
	v_pk_mul_f32 v[92:93], v[92:93], s[8:9] op_sel_hi:[1,0]
	v_pk_mul_f32 v[80:81], v[80:81], s[8:9] op_sel_hi:[1,0]
	v_pk_mul_f32 v[104:105], v[90:91], s[8:9] op_sel_hi:[1,0]
	v_pk_mul_f32 v[90:91], v[88:89], s[8:9] op_sel_hi:[1,0]
	v_cvt_pk_bf16_f32 v88, v96, v97
	v_cvt_pk_bf16_f32 v89, v98, v99
	v_pk_mul_f32 v[82:83], v[82:83], s[8:9] op_sel_hi:[1,0]
	v_cvt_pk_bf16_f32 v90, v90, v91
	v_cvt_pk_bf16_f32 v91, v104, v105
	global_store_dwordx4 v[112:113], v[88:91], off offset:256 sc1
	v_pk_mul_f32 v[78:79], v[78:79], s[8:9] op_sel_hi:[1,0]
	v_pk_mul_f32 v[76:77], v[76:77], s[8:9] op_sel_hi:[1,0]
	v_or_b32_e32 v88, 32, v152
	v_mad_i64_i32 v[88:89], s[20:21], v88, s48, v[140:141]
	v_lshl_add_u64 v[96:97], v[88:89], 0, v[142:143]
	v_pk_mul_f32 v[88:89], v[100:101], s[8:9] op_sel_hi:[1,0]
	v_pk_mul_f32 v[90:91], v[102:103], s[8:9] op_sel_hi:[1,0]
	v_cvt_pk_bf16_f32 v88, v88, v89
	v_pk_mul_f32 v[68:69], v[68:69], s[8:9] op_sel_hi:[1,0]
	v_cvt_pk_bf16_f32 v89, v90, v91
	v_cvt_pk_bf16_f32 v90, v92, v93
	v_cvt_pk_bf16_f32 v91, v94, v95
	global_store_dwordx4 v[96:97], v[88:91], off sc1
	v_pk_mul_f32 v[70:71], v[70:71], s[8:9] op_sel_hi:[1,0]
	v_pk_mul_f32 v[62:63], v[62:63], s[8:9] op_sel_hi:[1,0]
	v_pk_mul_f32 v[88:89], v[74:75], s[8:9] op_sel_hi:[1,0]
	v_pk_mul_f32 v[74:75], v[72:73], s[8:9] op_sel_hi:[1,0]
	v_cvt_pk_bf16_f32 v72, v80, v81
	v_cvt_pk_bf16_f32 v73, v82, v83
	v_pk_mul_f32 v[60:61], v[60:61], s[8:9] op_sel_hi:[1,0]
	v_cvt_pk_bf16_f32 v74, v74, v75
	v_cvt_pk_bf16_f32 v75, v88, v89
	global_store_dwordx4 v[96:97], v[72:75], off offset:256 sc1
	v_pk_mul_f32 v[48:49], v[48:49], s[8:9] op_sel_hi:[1,0]
	v_pk_mul_f32 v[50:51], v[50:51], s[8:9] op_sel_hi:[1,0]
	v_or_b32_e32 v72, 48, v152
	v_mad_i64_i32 v[72:73], s[20:21], v72, s48, v[140:141]
	v_lshl_add_u64 v[80:81], v[72:73], 0, v[142:143]
	v_pk_mul_f32 v[72:73], v[84:85], s[8:9] op_sel_hi:[1,0]
	v_pk_mul_f32 v[74:75], v[86:87], s[8:9] op_sel_hi:[1,0]
	v_cvt_pk_bf16_f32 v72, v72, v73
	v_pk_mul_f32 v[46:47], v[46:47], s[8:9] op_sel_hi:[1,0]
	v_cvt_pk_bf16_f32 v73, v74, v75
	v_cvt_pk_bf16_f32 v74, v76, v77
	v_cvt_pk_bf16_f32 v75, v78, v79
	global_store_dwordx4 v[80:81], v[72:75], off sc1
	v_pk_mul_f32 v[44:45], v[44:45], s[8:9] op_sel_hi:[1,0]
	v_pk_mul_f32 v[32:33], v[32:33], s[8:9] op_sel_hi:[1,0]
	v_pk_mul_f32 v[72:73], v[66:67], s[8:9] op_sel_hi:[1,0]
	v_pk_mul_f32 v[66:67], v[64:65], s[8:9] op_sel_hi:[1,0]
	v_cvt_pk_bf16_f32 v64, v68, v69
	v_cvt_pk_bf16_f32 v65, v70, v71
	v_pk_mul_f32 v[34:35], v[34:35], s[8:9] op_sel_hi:[1,0]
	v_cvt_pk_bf16_f32 v66, v66, v67
	v_cvt_pk_bf16_f32 v67, v72, v73
	global_store_dwordx4 v[80:81], v[64:67], off offset:256 sc1
	v_pk_mul_f32 v[30:31], v[30:31], s[8:9] op_sel_hi:[1,0]
	v_pk_mul_f32 v[28:29], v[28:29], s[8:9] op_sel_hi:[1,0]
	v_add_u32_e32 v64, 0x80, v152
	v_mad_i64_i32 v[64:65], s[20:21], v64, s48, v[140:141]
	v_lshl_add_u64 v[64:65], v[64:65], 0, v[142:143]
	v_pk_mul_f32 v[66:67], v[58:59], s[8:9] op_sel_hi:[1,0]
	v_pk_mul_f32 v[58:59], v[56:57], s[8:9] op_sel_hi:[1,0]
	v_cvt_pk_bf16_f32 v56, v60, v61
	v_cvt_pk_bf16_f32 v57, v62, v63
	v_pk_mul_f32 v[16:17], v[16:17], s[8:9] op_sel_hi:[1,0]
	v_cvt_pk_bf16_f32 v58, v58, v59
	v_cvt_pk_bf16_f32 v59, v66, v67
	global_store_dwordx4 v[64:65], v[56:59], off sc1
	v_pk_mul_f32 v[18:19], v[18:19], s[8:9] op_sel_hi:[1,0]
	v_pk_mul_f32 v[14:15], v[14:15], s[8:9] op_sel_hi:[1,0]
	v_pk_mul_f32 v[56:57], v[42:43], s[8:9] op_sel_hi:[1,0]
	v_pk_mul_f32 v[42:43], v[40:41], s[8:9] op_sel_hi:[1,0]
	v_cvt_pk_bf16_f32 v40, v48, v49
	v_cvt_pk_bf16_f32 v41, v50, v51
	v_pk_mul_f32 v[12:13], v[12:13], s[8:9] op_sel_hi:[1,0]
	v_cvt_pk_bf16_f32 v42, v42, v43
	v_cvt_pk_bf16_f32 v43, v56, v57
	global_store_dwordx4 v[64:65], v[40:43], off offset:256 sc1
	s_and_b64 vcc, exec, s[10:11]
	s_mov_b32 s54, s50
	v_add_u32_e32 v40, 0x90, v152
	v_mad_i64_i32 v[40:41], s[20:21], v40, s48, v[140:141]
	v_lshl_add_u64 v[48:49], v[40:41], 0, v[142:143]
	v_pk_mul_f32 v[40:41], v[52:53], s[8:9] op_sel_hi:[1,0]
	v_pk_mul_f32 v[42:43], v[54:55], s[8:9] op_sel_hi:[1,0]
	v_cvt_pk_bf16_f32 v40, v40, v41
	s_mov_b32 s53, s49
	v_cvt_pk_bf16_f32 v41, v42, v43
	v_cvt_pk_bf16_f32 v42, v44, v45
	v_cvt_pk_bf16_f32 v43, v46, v47
	global_store_dwordx4 v[48:49], v[40:43], off sc1
	s_mov_b32 s26, s52
	v_pk_mul_f32 v[6:7], v[6:7], s[8:9] op_sel_hi:[1,0]
	v_pk_mul_f32 v[40:41], v[26:27], s[8:9] op_sel_hi:[1,0]
	v_pk_mul_f32 v[26:27], v[24:25], s[8:9] op_sel_hi:[1,0]
	v_cvt_pk_bf16_f32 v24, v32, v33
	v_cvt_pk_bf16_f32 v25, v34, v35
	v_pk_mul_f32 v[4:5], v[4:5], s[8:9] op_sel_hi:[1,0]
	v_cvt_pk_bf16_f32 v26, v26, v27
	v_cvt_pk_bf16_f32 v27, v40, v41
	global_store_dwordx4 v[48:49], v[24:27], off offset:256 sc1
	s_nop 1
	v_add_u32_e32 v24, 0xa0, v152
	v_mad_i64_i32 v[24:25], s[20:21], v24, s48, v[140:141]
	v_lshl_add_u64 v[32:33], v[24:25], 0, v[142:143]
	v_pk_mul_f32 v[24:25], v[36:37], s[8:9] op_sel_hi:[1,0]
	v_pk_mul_f32 v[26:27], v[38:39], s[8:9] op_sel_hi:[1,0]
	v_cvt_pk_bf16_f32 v24, v24, v25
	s_nop 0
	v_cvt_pk_bf16_f32 v25, v26, v27
	v_cvt_pk_bf16_f32 v26, v28, v29
	v_cvt_pk_bf16_f32 v27, v30, v31
	global_store_dwordx4 v[32:33], v[24:27], off sc1
	s_nop 1
	v_pk_mul_f32 v[24:25], v[10:11], s[8:9] op_sel_hi:[1,0]
	v_pk_mul_f32 v[10:11], v[8:9], s[8:9] op_sel_hi:[1,0]
	v_cvt_pk_bf16_f32 v8, v16, v17
	v_cvt_pk_bf16_f32 v9, v18, v19
	s_nop 0
	v_cvt_pk_bf16_f32 v10, v10, v11
	v_cvt_pk_bf16_f32 v11, v24, v25
	global_store_dwordx4 v[32:33], v[8:11], off offset:256 sc1
	s_nop 1
	v_add_u32_e32 v8, 0xb0, v152
	v_mad_i64_i32 v[8:9], s[20:21], v8, s48, v[140:141]
	v_lshl_add_u64 v[16:17], v[8:9], 0, v[142:143]
	v_pk_mul_f32 v[8:9], v[20:21], s[8:9] op_sel_hi:[1,0]
	v_pk_mul_f32 v[10:11], v[22:23], s[8:9] op_sel_hi:[1,0]
	v_cvt_pk_bf16_f32 v8, v8, v9
	s_mov_b32 s20, s51
	v_cvt_pk_bf16_f32 v9, v10, v11
	v_cvt_pk_bf16_f32 v10, v12, v13
	v_cvt_pk_bf16_f32 v11, v14, v15
	global_store_dwordx4 v[16:17], v[8:11], off sc1
	s_nop 1
	v_pk_mul_f32 v[8:9], v[2:3], s[8:9] op_sel_hi:[1,0]
	v_pk_mul_f32 v[2:3], v[0:1], s[8:9] op_sel_hi:[1,0]
	v_cvt_pk_bf16_f32 v0, v4, v5
	v_cvt_pk_bf16_f32 v1, v6, v7
	s_nop 0
	v_cvt_pk_bf16_f32 v2, v2, v3
	v_cvt_pk_bf16_f32 v3, v8, v9
	global_store_dwordx4 v[16:17], v[0:3], off offset:256 sc1
	s_cbranch_vccnz .LBB0_612

.LBB0_617:
	v_readfirstlane_b32 s11, v140
	s_lshl_b32 s21, s11, 4
	s_andn2_b32 s21, s21, 63
	v_mbcnt_lo_u32_b32 v137, -1, 0
	v_mbcnt_hi_u32_b32 v137, -1, v137
	s_add_i32 s21, s21, s20
	s_lshl_b32 s11, s11, 5
	v_and_or_b32 v136, v137, 15, s21
	s_and_b32 s11, s11, 0x60
	v_ashrrev_i32_e32 v137, 1, v137
	v_and_b32_e32 v137, -8, v137
	s_or_b32 s10, s11, s10
	v_add_u32_e32 v138, s10, v137
	v_ashrrev_i32_e32 v137, 31, v136
	v_lshlrev_b64 v[144:145], 11, v[136:137]
	v_ashrrev_i32_e32 v139, 31, v138
	v_lshl_add_u64 v[144:145], s[4:5], 0, v[144:145]
	v_lshlrev_b64 v[138:139], 1, v[138:139]
	v_lshl_add_u64 v[144:145], v[144:145], 0, v[138:139]
	v_cvt_pk_bf16_f32 v116, v116, v117
	v_cvt_pk_bf16_f32 v117, v118, v119
	v_cvt_pk_bf16_f32 v118, v112, v113
	v_cvt_pk_bf16_f32 v112, v124, v125
	v_cvt_pk_bf16_f32 v119, v114, v115
	v_cvt_pk_bf16_f32 v113, v126, v127
	v_cvt_pk_bf16_f32 v114, v120, v121
	v_cvt_pk_bf16_f32 v115, v122, v123
	global_store_dwordx4 v[144:145], v[112:115], off offset:256 sc1
	v_cvt_pk_bf16_f32 v100, v100, v101
	v_cvt_pk_bf16_f32 v101, v102, v103
	v_cvt_pk_bf16_f32 v102, v96, v97
	v_cvt_pk_bf16_f32 v96, v108, v109
	v_cvt_pk_bf16_f32 v103, v98, v99
	s_nop 1
	v_or_b32_e32 v112, 16, v136
	v_ashrrev_i32_e32 v113, 31, v112
	v_lshlrev_b64 v[112:113], 11, v[112:113]
	v_lshl_add_u64 v[112:113], s[4:5], 0, v[112:113]
	v_lshl_add_u64 v[112:113], v[112:113], 0, v[138:139]
	v_cvt_pk_bf16_f32 v97, v110, v111
	v_cvt_pk_bf16_f32 v98, v104, v105
	v_cvt_pk_bf16_f32 v99, v106, v107
	global_store_dwordx4 v[112:113], v[96:99], off offset:256 sc1
	v_cvt_pk_bf16_f32 v84, v84, v85
	v_cvt_pk_bf16_f32 v85, v86, v87
	v_cvt_pk_bf16_f32 v86, v80, v81
	v_cvt_pk_bf16_f32 v80, v92, v93
	v_cvt_pk_bf16_f32 v87, v82, v83
	s_nop 1
	v_or_b32_e32 v96, 32, v136
	v_ashrrev_i32_e32 v97, 31, v96
	v_lshlrev_b64 v[96:97], 11, v[96:97]
	v_lshl_add_u64 v[96:97], s[4:5], 0, v[96:97]
	v_lshl_add_u64 v[96:97], v[96:97], 0, v[138:139]
	v_cvt_pk_bf16_f32 v81, v94, v95
	v_cvt_pk_bf16_f32 v82, v88, v89
	v_cvt_pk_bf16_f32 v83, v90, v91
	global_store_dwordx4 v[96:97], v[80:83], off offset:256 sc1
	v_cvt_pk_bf16_f32 v60, v60, v61
	v_cvt_pk_bf16_f32 v61, v62, v63
	v_cvt_pk_bf16_f32 v62, v48, v49
	v_cvt_pk_bf16_f32 v48, v76, v77
	v_cvt_pk_bf16_f32 v63, v50, v51
	s_nop 1
	v_or_b32_e32 v80, 48, v136
	v_ashrrev_i32_e32 v81, 31, v80
	v_lshlrev_b64 v[80:81], 11, v[80:81]
	v_lshl_add_u64 v[80:81], s[4:5], 0, v[80:81]
	v_lshl_add_u64 v[80:81], v[80:81], 0, v[138:139]
	v_cvt_pk_bf16_f32 v49, v78, v79
	v_cvt_pk_bf16_f32 v50, v72, v73
	v_cvt_pk_bf16_f32 v51, v74, v75
	global_store_dwordx4 v[80:81], v[48:51], off offset:256 sc1
	global_store_dwordx4 v[80:81], v[60:63], off sc1
	v_cvt_pk_bf16_f32 v40, v40, v41
	v_cvt_pk_bf16_f32 v41, v42, v43
	v_cvt_pk_bf16_f32 v42, v32, v33
	v_cvt_pk_bf16_f32 v32, v44, v45
	s_nop 0
	v_add_u32_e32 v48, 0x80, v136
	v_ashrrev_i32_e32 v49, 31, v48
	v_lshlrev_b64 v[48:49], 11, v[48:49]
	v_lshl_add_u64 v[48:49], s[4:5], 0, v[48:49]
	v_lshl_add_u64 v[60:61], v[48:49], 0, v[138:139]
	v_cvt_pk_bf16_f32 v48, v64, v65
	v_cvt_pk_bf16_f32 v49, v66, v67
	v_cvt_pk_bf16_f32 v50, v52, v53
	v_cvt_pk_bf16_f32 v51, v54, v55
	global_store_dwordx4 v[60:61], v[48:51], off sc1
	v_cvt_pk_bf16_f32 v43, v34, v35
	v_cvt_pk_bf16_f32 v33, v46, v47
	v_cvt_pk_bf16_f32 v34, v36, v37
	v_cvt_pk_bf16_f32 v35, v38, v39
	v_cvt_pk_bf16_f32 v24, v24, v25
	s_nop 1
	v_cvt_pk_bf16_f32 v48, v68, v69
	v_cvt_pk_bf16_f32 v49, v70, v71
	v_cvt_pk_bf16_f32 v50, v56, v57
	v_cvt_pk_bf16_f32 v51, v58, v59
	global_store_dwordx4 v[60:61], v[48:51], off offset:256 sc1
	v_cvt_pk_bf16_f32 v25, v26, v27
	v_cvt_pk_bf16_f32 v26, v16, v17
	v_cvt_pk_bf16_f32 v16, v28, v29
	v_cvt_pk_bf16_f32 v27, v18, v19
	v_cvt_pk_bf16_f32 v17, v30, v31
	s_nop 1
	v_add_u32_e32 v48, 0x90, v136
	v_ashrrev_i32_e32 v49, 31, v48
	v_lshlrev_b64 v[48:49], 11, v[48:49]
	v_lshl_add_u64 v[48:49], s[4:5], 0, v[48:49]
	v_lshl_add_u64 v[48:49], v[48:49], 0, v[138:139]
	global_store_dwordx4 v[48:49], v[32:35], off offset:256 sc1
	v_cvt_pk_bf16_f32 v18, v20, v21
	v_cvt_pk_bf16_f32 v19, v22, v23
	s_andn2_b64 vcc, exec, s[8:9]
	global_store_dwordx4 v[144:145], v[116:119], off sc1
	v_add_u32_e32 v32, 0xa0, v136
	v_ashrrev_i32_e32 v33, 31, v32
	v_lshlrev_b64 v[32:33], 11, v[32:33]
	v_lshl_add_u64 v[32:33], s[4:5], 0, v[32:33]
	v_lshl_add_u64 v[32:33], v[32:33], 0, v[138:139]
	global_store_dwordx4 v[32:33], v[16:19], off offset:256 sc1
	global_store_dwordx4 v[112:113], v[100:103], off sc1
	global_store_dwordx4 v[96:97], v[84:87], off sc1
	v_add_u32_e32 v16, 0xb0, v136
	v_ashrrev_i32_e32 v17, 31, v16
	v_lshlrev_b64 v[16:17], 11, v[16:17]
	v_lshl_add_u64 v[16:17], s[4:5], 0, v[16:17]
	v_lshl_add_u64 v[16:17], v[16:17], 0, v[138:139]
	global_store_dwordx4 v[48:49], v[40:43], off sc1
	global_store_dwordx4 v[32:33], v[24:27], off sc1
	v_cvt_pk_bf16_f32 v8, v8, v9
	v_cvt_pk_bf16_f32 v9, v10, v11
	v_cvt_pk_bf16_f32 v10, v0, v1
	v_cvt_pk_bf16_f32 v11, v2, v3
	global_store_dwordx4 v[16:17], v[8:11], off sc1
	v_cvt_pk_bf16_f32 v0, v12, v13
	v_cvt_pk_bf16_f32 v1, v14, v15
	v_cvt_pk_bf16_f32 v2, v4, v5
	v_cvt_pk_bf16_f32 v3, v6, v7
	global_store_dwordx4 v[16:17], v[0:3], off offset:256 sc1
	s_cbranch_vccz .LBB0_624

.LBB0_696:
	v_readfirstlane_b32 s2, v145
	s_lshl_b32 s11, s2, 4
	s_lshl_b32 s10, s50, 8
	s_andn2_b32 s11, s11, 63
	v_mbcnt_lo_u32_b32 v141, -1, 0
	v_mbcnt_hi_u32_b32 v141, -1, v141
	s_add_i32 s11, s11, s10
	s_lshl_b32 s2, s2, 5
	v_and_or_b32 v140, v141, 15, s11
	s_lshl_b32 s10, s49, 8
	s_and_b32 s2, s2, 0x60
	v_ashrrev_i32_e32 v141, 1, v141
	v_and_b32_e32 v141, -8, v141
	s_or_b32 s2, s2, s10
	v_cvt_pk_bf16_f32 v68, v68, v69
	v_cvt_pk_bf16_f32 v69, v70, v71
	v_cvt_pk_bf16_f32 v70, v64, v65
	v_add_u32_e32 v64, 0x80, v140
	v_add_u32_e32 v142, s2, v141
	v_ashrrev_i32_e32 v141, 31, v140
	v_cvt_pk_bf16_f32 v108, v108, v109
	v_cvt_pk_bf16_f32 v109, v110, v111
	v_cvt_pk_bf16_f32 v110, v104, v105
	v_or_b32_e32 v104, 16, v140
	v_ashrrev_i32_e32 v65, 31, v64
	v_cvt_pk_bf16_f32 v44, v44, v45
	v_cvt_pk_bf16_f32 v45, v46, v47
	v_cvt_pk_bf16_f32 v46, v40, v41
	v_add_u32_e32 v40, 0x90, v140
	v_lshlrev_b64 v[148:149], 11, v[140:141]
	v_ashrrev_i32_e32 v143, 31, v142
	v_ashrrev_i32_e32 v105, 31, v104
	v_cvt_pk_bf16_f32 v92, v92, v93
	v_cvt_pk_bf16_f32 v93, v94, v95
	v_cvt_pk_bf16_f32 v94, v88, v89
	v_or_b32_e32 v88, 32, v140
	v_lshlrev_b64 v[64:65], 11, v[64:65]
	v_ashrrev_i32_e32 v41, 31, v40
	v_cvt_pk_bf16_f32 v28, v28, v29
	v_cvt_pk_bf16_f32 v29, v30, v31
	v_cvt_pk_bf16_f32 v30, v24, v25
	v_add_u32_e32 v24, 0xa0, v140
	v_lshl_add_u64 v[148:149], s[0:1], 0, v[148:149]
	v_lshlrev_b64 v[142:143], 1, v[142:143]
	v_lshlrev_b64 v[104:105], 11, v[104:105]
	v_ashrrev_i32_e32 v89, 31, v88
	v_cvt_pk_bf16_f32 v76, v76, v77
	v_cvt_pk_bf16_f32 v77, v78, v79
	v_cvt_pk_bf16_f32 v78, v72, v73
	v_or_b32_e32 v72, 48, v140
	v_lshl_add_u64 v[64:65], s[0:1], 0, v[64:65]
	v_lshlrev_b64 v[40:41], 11, v[40:41]
	v_ashrrev_i32_e32 v25, 31, v24
	v_cvt_pk_bf16_f32 v12, v12, v13
	v_cvt_pk_bf16_f32 v13, v14, v15
	v_cvt_pk_bf16_f32 v14, v8, v9
	v_add_u32_e32 v8, 0xb0, v140
	v_lshl_add_u64 v[148:149], v[148:149], 0, v[142:143]
	v_lshl_add_u64 v[104:105], s[0:1], 0, v[104:105]
	v_lshlrev_b64 v[88:89], 11, v[88:89]
	v_ashrrev_i32_e32 v73, 31, v72
	v_lshl_add_u64 v[64:65], v[64:65], 0, v[142:143]
	v_lshl_add_u64 v[40:41], s[0:1], 0, v[40:41]
	v_lshlrev_b64 v[24:25], 11, v[24:25]
	v_ashrrev_i32_e32 v9, 31, v8
	v_cvt_pk_bf16_f32 v111, v106, v107
	global_store_dwordx4 v[148:149], v[108:111], off offset:256 sc1
	v_lshl_add_u64 v[88:89], s[0:1], 0, v[88:89]
	v_lshlrev_b64 v[72:73], 11, v[72:73]
	v_lshl_add_u64 v[108:109], v[104:105], 0, v[142:143]
	v_cvt_pk_bf16_f32 v47, v42, v43
	global_store_dwordx4 v[64:65], v[44:47], off offset:256 sc1
	v_lshl_add_u64 v[24:25], s[0:1], 0, v[24:25]
	v_lshlrev_b64 v[8:9], 11, v[8:9]
	v_lshl_add_u64 v[44:45], v[40:41], 0, v[142:143]
	v_cvt_pk_bf16_f32 v95, v90, v91
	global_store_dwordx4 v[108:109], v[92:95], off offset:256 sc1
	v_lshl_add_u64 v[72:73], s[0:1], 0, v[72:73]
	v_cvt_pk_bf16_f32 v31, v26, v27
	global_store_dwordx4 v[44:45], v[28:31], off offset:256 sc1
	v_lshl_add_u64 v[92:93], v[88:89], 0, v[142:143]
	v_lshl_add_u64 v[8:9], s[0:1], 0, v[8:9]
	v_lshl_add_u64 v[28:29], v[24:25], 0, v[142:143]
	v_cvt_pk_bf16_f32 v79, v74, v75
	global_store_dwordx4 v[92:93], v[76:79], off offset:256 sc1
	v_cvt_pk_bf16_f32 v15, v10, v11
	global_store_dwordx4 v[28:29], v[12:15], off offset:256 sc1
	s_and_b64 vcc, exec, s[8:9]
	v_lshl_add_u64 v[76:77], v[72:73], 0, v[142:143]
	v_lshl_add_u64 v[12:13], v[8:9], 0, v[142:143]
	s_mov_b32 s50, s52
	s_mov_b32 s49, s51
	s_mov_b32 s10, s53
	s_mov_b32 s16, s54
	v_cvt_pk_bf16_f32 v124, v124, v125
	v_cvt_pk_bf16_f32 v125, v126, v127
	v_cvt_pk_bf16_f32 v126, v120, v121
	v_cvt_pk_bf16_f32 v127, v122, v123
	global_store_dwordx4 v[148:149], v[124:127], off sc1
	v_cvt_pk_bf16_f32 v104, v116, v117
	v_cvt_pk_bf16_f32 v105, v118, v119
	v_cvt_pk_bf16_f32 v106, v112, v113
	v_cvt_pk_bf16_f32 v107, v114, v115
	global_store_dwordx4 v[108:109], v[104:107], off sc1
	v_cvt_pk_bf16_f32 v88, v100, v101
	v_cvt_pk_bf16_f32 v89, v102, v103
	v_cvt_pk_bf16_f32 v90, v96, v97
	v_cvt_pk_bf16_f32 v91, v98, v99
	global_store_dwordx4 v[92:93], v[88:91], off sc1
	v_cvt_pk_bf16_f32 v72, v84, v85
	v_cvt_pk_bf16_f32 v73, v86, v87
	v_cvt_pk_bf16_f32 v74, v80, v81
	v_cvt_pk_bf16_f32 v75, v82, v83
	global_store_dwordx4 v[76:77], v[72:75], off sc1
	v_cvt_pk_bf16_f32 v71, v66, v67
	global_store_dwordx4 v[76:77], v[68:71], off offset:256 sc1
	v_cvt_pk_bf16_f32 v60, v60, v61
	v_cvt_pk_bf16_f32 v61, v62, v63
	v_cvt_pk_bf16_f32 v62, v56, v57
	v_cvt_pk_bf16_f32 v63, v58, v59
	global_store_dwordx4 v[64:65], v[60:63], off sc1
	v_cvt_pk_bf16_f32 v40, v52, v53
	v_cvt_pk_bf16_f32 v41, v54, v55
	v_cvt_pk_bf16_f32 v42, v48, v49
	v_cvt_pk_bf16_f32 v43, v50, v51
	global_store_dwordx4 v[44:45], v[40:43], off sc1
	v_cvt_pk_bf16_f32 v24, v36, v37
	v_cvt_pk_bf16_f32 v25, v38, v39
	v_cvt_pk_bf16_f32 v26, v32, v33
	v_cvt_pk_bf16_f32 v27, v34, v35
	global_store_dwordx4 v[28:29], v[24:27], off sc1
	v_cvt_pk_bf16_f32 v8, v20, v21
	v_cvt_pk_bf16_f32 v9, v22, v23
	v_cvt_pk_bf16_f32 v10, v16, v17
	v_cvt_pk_bf16_f32 v11, v18, v19
	global_store_dwordx4 v[12:13], v[8:11], off sc1
	v_cvt_pk_bf16_f32 v4, v4, v5
	v_cvt_pk_bf16_f32 v5, v6, v7
	v_cvt_pk_bf16_f32 v6, v0, v1
	v_cvt_pk_bf16_f32 v7, v2, v3
	global_store_dwordx4 v[12:13], v[4:7], off offset:256 sc1
	s_cbranch_vccnz .LBB0_703

.LBB0_759:
	v_readfirstlane_b32 s2, v145
	s_lshl_b32 s9, s2, 4
	s_lshl_b32 s8, s48, 8
	s_andn2_b32 s9, s9, 63
	v_mbcnt_lo_u32_b32 v141, -1, 0
	v_mbcnt_hi_u32_b32 v141, -1, v141
	s_add_i32 s9, s9, s8
	s_lshl_b32 s2, s2, 5
	v_and_or_b32 v140, v141, 15, s9
	s_lshl_b32 s8, s47, 8
	s_and_b32 s2, s2, 0x60
	v_ashrrev_i32_e32 v141, 1, v141
	v_and_b32_e32 v141, -8, v141
	s_or_b32 s2, s2, s8
	v_cvt_pk_bf16_f32 v68, v68, v69
	v_cvt_pk_bf16_f32 v69, v70, v71
	v_cvt_pk_bf16_f32 v70, v64, v65
	v_add_u32_e32 v64, 0x80, v140
	v_add_u32_e32 v142, s2, v141
	v_ashrrev_i32_e32 v141, 31, v140
	v_cvt_pk_bf16_f32 v108, v108, v109
	v_cvt_pk_bf16_f32 v109, v110, v111
	v_cvt_pk_bf16_f32 v110, v104, v105
	v_or_b32_e32 v104, 16, v140
	v_ashrrev_i32_e32 v65, 31, v64
	v_cvt_pk_bf16_f32 v44, v44, v45
	v_cvt_pk_bf16_f32 v45, v46, v47
	v_cvt_pk_bf16_f32 v46, v40, v41
	v_add_u32_e32 v40, 0x90, v140
	v_lshlrev_b64 v[148:149], 11, v[140:141]
	v_ashrrev_i32_e32 v143, 31, v142
	v_ashrrev_i32_e32 v105, 31, v104
	v_cvt_pk_bf16_f32 v92, v92, v93
	v_cvt_pk_bf16_f32 v93, v94, v95
	v_cvt_pk_bf16_f32 v94, v88, v89
	v_or_b32_e32 v88, 32, v140
	v_lshlrev_b64 v[64:65], 11, v[64:65]
	v_ashrrev_i32_e32 v41, 31, v40
	v_cvt_pk_bf16_f32 v28, v28, v29
	v_cvt_pk_bf16_f32 v29, v30, v31
	v_cvt_pk_bf16_f32 v30, v24, v25
	v_add_u32_e32 v24, 0xa0, v140
	v_lshl_add_u64 v[148:149], s[0:1], 0, v[148:149]
	v_lshlrev_b64 v[142:143], 1, v[142:143]
	v_lshlrev_b64 v[104:105], 11, v[104:105]
	v_ashrrev_i32_e32 v89, 31, v88
	v_cvt_pk_bf16_f32 v76, v76, v77
	v_cvt_pk_bf16_f32 v77, v78, v79
	v_cvt_pk_bf16_f32 v78, v72, v73
	v_or_b32_e32 v72, 48, v140
	v_lshl_add_u64 v[64:65], s[0:1], 0, v[64:65]
	v_lshlrev_b64 v[40:41], 11, v[40:41]
	v_ashrrev_i32_e32 v25, 31, v24
	v_cvt_pk_bf16_f32 v12, v12, v13
	v_cvt_pk_bf16_f32 v13, v14, v15
	v_cvt_pk_bf16_f32 v14, v8, v9
	v_add_u32_e32 v8, 0xb0, v140
	v_lshl_add_u64 v[148:149], v[148:149], 0, v[142:143]
	v_lshl_add_u64 v[104:105], s[0:1], 0, v[104:105]
	v_lshlrev_b64 v[88:89], 11, v[88:89]
	v_ashrrev_i32_e32 v73, 31, v72
	v_lshl_add_u64 v[64:65], v[64:65], 0, v[142:143]
	v_lshl_add_u64 v[40:41], s[0:1], 0, v[40:41]
	v_lshlrev_b64 v[24:25], 11, v[24:25]
	v_ashrrev_i32_e32 v9, 31, v8
	v_cvt_pk_bf16_f32 v111, v106, v107
	global_store_dwordx4 v[148:149], v[108:111], off offset:256 sc1
	v_lshl_add_u64 v[88:89], s[0:1], 0, v[88:89]
	v_lshlrev_b64 v[72:73], 11, v[72:73]
	v_lshl_add_u64 v[108:109], v[104:105], 0, v[142:143]
	v_cvt_pk_bf16_f32 v47, v42, v43
	global_store_dwordx4 v[64:65], v[44:47], off offset:256 sc1
	v_lshl_add_u64 v[24:25], s[0:1], 0, v[24:25]
	v_lshlrev_b64 v[8:9], 11, v[8:9]
	v_lshl_add_u64 v[44:45], v[40:41], 0, v[142:143]
	v_cvt_pk_bf16_f32 v95, v90, v91
	global_store_dwordx4 v[108:109], v[92:95], off offset:256 sc1
	v_lshl_add_u64 v[72:73], s[0:1], 0, v[72:73]
	v_cvt_pk_bf16_f32 v31, v26, v27
	global_store_dwordx4 v[44:45], v[28:31], off offset:256 sc1
	v_lshl_add_u64 v[92:93], v[88:89], 0, v[142:143]
	v_lshl_add_u64 v[8:9], s[0:1], 0, v[8:9]
	v_lshl_add_u64 v[28:29], v[24:25], 0, v[142:143]
	v_cvt_pk_bf16_f32 v79, v74, v75
	global_store_dwordx4 v[92:93], v[76:79], off offset:256 sc1
	v_cvt_pk_bf16_f32 v15, v10, v11
	global_store_dwordx4 v[28:29], v[12:15], off offset:256 sc1
	s_and_b64 vcc, exec, s[6:7]
	v_lshl_add_u64 v[76:77], v[72:73], 0, v[142:143]
	v_lshl_add_u64 v[12:13], v[8:9], 0, v[142:143]
	s_mov_b32 s48, s50
	s_mov_b32 s47, s49
	s_mov_b32 s8, s51
	s_mov_b32 s10, s52
	v_cvt_pk_bf16_f32 v124, v124, v125
	v_cvt_pk_bf16_f32 v125, v126, v127
	v_cvt_pk_bf16_f32 v126, v120, v121
	v_cvt_pk_bf16_f32 v127, v122, v123
	global_store_dwordx4 v[148:149], v[124:127], off sc1
	v_cvt_pk_bf16_f32 v104, v116, v117
	v_cvt_pk_bf16_f32 v105, v118, v119
	v_cvt_pk_bf16_f32 v106, v112, v113
	v_cvt_pk_bf16_f32 v107, v114, v115
	global_store_dwordx4 v[108:109], v[104:107], off sc1
	v_cvt_pk_bf16_f32 v88, v100, v101
	v_cvt_pk_bf16_f32 v89, v102, v103
	v_cvt_pk_bf16_f32 v90, v96, v97
	v_cvt_pk_bf16_f32 v91, v98, v99
	global_store_dwordx4 v[92:93], v[88:91], off sc1
	v_cvt_pk_bf16_f32 v72, v84, v85
	v_cvt_pk_bf16_f32 v73, v86, v87
	v_cvt_pk_bf16_f32 v74, v80, v81
	v_cvt_pk_bf16_f32 v75, v82, v83
	global_store_dwordx4 v[76:77], v[72:75], off sc1
	v_cvt_pk_bf16_f32 v71, v66, v67
	global_store_dwordx4 v[76:77], v[68:71], off offset:256 sc1
	v_cvt_pk_bf16_f32 v60, v60, v61
	v_cvt_pk_bf16_f32 v61, v62, v63
	v_cvt_pk_bf16_f32 v62, v56, v57
	v_cvt_pk_bf16_f32 v63, v58, v59
	global_store_dwordx4 v[64:65], v[60:63], off sc1
	v_cvt_pk_bf16_f32 v40, v52, v53
	v_cvt_pk_bf16_f32 v41, v54, v55
	v_cvt_pk_bf16_f32 v42, v48, v49
	v_cvt_pk_bf16_f32 v43, v50, v51
	global_store_dwordx4 v[44:45], v[40:43], off sc1
	v_cvt_pk_bf16_f32 v24, v36, v37
	v_cvt_pk_bf16_f32 v25, v38, v39
	v_cvt_pk_bf16_f32 v26, v32, v33
	v_cvt_pk_bf16_f32 v27, v34, v35
	global_store_dwordx4 v[28:29], v[24:27], off sc1
	v_cvt_pk_bf16_f32 v8, v20, v21
	v_cvt_pk_bf16_f32 v9, v22, v23
	v_cvt_pk_bf16_f32 v10, v16, v17
	v_cvt_pk_bf16_f32 v11, v18, v19
	global_store_dwordx4 v[12:13], v[8:11], off sc1
	v_cvt_pk_bf16_f32 v4, v4, v5
	v_cvt_pk_bf16_f32 v5, v6, v7
	v_cvt_pk_bf16_f32 v6, v0, v1
	v_cvt_pk_bf16_f32 v7, v2, v3
	global_store_dwordx4 v[12:13], v[4:7], off offset:256 sc1
	s_cbranch_vccnz .LBB0_766
